# fused-epilogue row-sum reductions use v_permlane16/32_swap instead of two serialized ds_bpermute round trips per chunk
# speedup vs baseline: 1.0038x; 1.0023x over previous
; __device__ __forceinline__ void panel_rstd(const f32x4 (&v)[2][2][4][2], const Unit& u, int wr, int wc, int fr, int fq, PG8_LAS unsigned char* lds, int wid, int lane,
;                                            float* xslots, unsigned* cnt, unsigned want, float eps) {
;     ...
; #pragma unroll
;     for (int ai = 0; ai < 2; ++ai)
; #pragma unroll
;         for (int m = 0; m < 4; ++m) {
;             float s = 0.f;
; #pragma unroll
;             for (int bj = 0; bj < 2; ++bj)
; #pragma unroll
;                 for (int n = 0; n < 2; ++n) { const f32x4 x = v[ai][bj][m][n]; s += (x[0] * x[0] + x[1] * x[1]) + (x[2] * x[2] + x[3] * x[3]); }
;             s += __shfl_xor(s, 16); s += __shfl_xor(s, 32);
;             if (fq == 0) P[(ai * HALF + wr * 64 + m * 16 + fr) * 4 + wc] = s;
;         }
.LBB0_725:
	s_barrier
	v_mul_f32_e32 v207, v97, v97
	v_mul_f32_e32 v208, v99, v99
	v_fmac_f32_e32 v207, v96, v96
	v_fmac_f32_e32 v208, v98, v98
	v_add_f32_e32 v207, v207, v208
	v_mul_f32_e32 v208, v161, v161
	v_mul_f32_e32 v209, v163, v163
	v_fmac_f32_e32 v208, v160, v160
	v_fmac_f32_e32 v209, v162, v162
	v_add_f32_e32 v208, v208, v209
	v_add_f32_e32 v207, v208, v207
	v_mul_f32_e32 v208, v85, v85
	v_mul_f32_e32 v209, v87, v87
	v_fmac_f32_e32 v208, v84, v84
	v_fmac_f32_e32 v209, v86, v86
	v_add_f32_e32 v208, v208, v209
	v_xor_b32_e32 v2, 16, v225
	v_add_f32_e32 v207, v208, v207
	v_mul_f32_e32 v208, v33, v33
	v_mul_f32_e32 v209, v35, v35
	v_cmp_lt_i32_e32 vcc, v2, v230
	v_fmac_f32_e32 v208, v32, v32
	v_fmac_f32_e32 v209, v34, v34
	v_cndmask_b32_e32 v2, v225, v2, vcc
	v_add_f32_e32 v208, v208, v209
	v_lshlrev_b32_e32 v2, 2, v2
	v_add_f32_e32 v207, v208, v207
	v_mov_b32_e32 v208, v207
	s_nop 1
	v_permlane16_swap_b32_e32 v208, v207
	v_xor_b32_e32 v209, 32, v225
	v_cmp_lt_i32_e32 vcc, v209, v230
	s_lshl_b32 s4, s26, 2
	s_add_i32 s48, s4, 0
	v_cndmask_b32_e32 v209, v225, v209, vcc
	v_lshlrev_b32_e32 v221, 2, v209
	s_waitcnt lgkmcnt(0)
	v_add_f32_e32 v207, v207, v208
	v_mov_b32_e32 v209, v207
	s_nop 1
	v_permlane32_swap_b32_e32 v209, v207
	v_and_b32_e32 v208, 63, v206
	v_cmp_gt_u32_e64 s[0:1], 16, v208
	s_and_saveexec_b64 s[4:5], s[0:1]
	s_cbranch_execz .LBB0_727
	s_lshl_b32 s6, s38, 10
	s_add_i32 s6, s48, s6
	v_lshl_add_u32 v210, v219, 4, s6
	s_waitcnt lgkmcnt(0)
	v_add_f32_e32 v207, v207, v209
	ds_write_b32 v210, v207
.LBB0_727:
	s_or_b64 exec, exec, s[4:5]
	v_mul_f32_e32 v207, v89, v89
	s_waitcnt lgkmcnt(0)
	v_mul_f32_e32 v209, v91, v91
	v_fmac_f32_e32 v207, v88, v88
	v_fmac_f32_e32 v209, v90, v90
	v_add_f32_e32 v207, v207, v209
	v_mul_f32_e32 v209, v157, v157
	v_mul_f32_e32 v210, v159, v159
	v_fmac_f32_e32 v209, v156, v156
	v_fmac_f32_e32 v210, v158, v158
	v_add_f32_e32 v209, v209, v210
	v_add_f32_e32 v207, v209, v207
	v_mul_f32_e32 v209, v77, v77
	v_mul_f32_e32 v210, v79, v79
	v_fmac_f32_e32 v209, v76, v76
	v_fmac_f32_e32 v210, v78, v78
	v_add_f32_e32 v209, v209, v210
	v_add_f32_e32 v207, v209, v207
	v_mul_f32_e32 v209, v29, v29
	v_mul_f32_e32 v210, v31, v31
	v_fmac_f32_e32 v209, v28, v28
	v_fmac_f32_e32 v210, v30, v30
	v_add_f32_e32 v209, v209, v210
	v_add_f32_e32 v207, v209, v207
	v_mov_b32_e32 v209, v207
	s_nop 1
	v_permlane16_swap_b32_e32 v209, v207
	s_waitcnt lgkmcnt(0)
	v_add_f32_e32 v207, v207, v209
	v_mov_b32_e32 v209, v207
	s_nop 1
	v_permlane32_swap_b32_e32 v209, v207
	s_and_saveexec_b64 s[4:5], s[0:1]
	s_cbranch_execz .LBB0_729
	s_lshl_b32 s6, s38, 10
	s_add_i32 s6, s48, s6
	v_lshl_add_u32 v210, v219, 4, s6
	s_waitcnt lgkmcnt(0)
	v_add_f32_e32 v207, v207, v209
	ds_write_b32 v210, v207 offset:256
.LBB0_729:
	s_or_b64 exec, exec, s[4:5]
	v_mul_f32_e32 v207, v93, v93
	s_waitcnt lgkmcnt(0)
	v_mul_f32_e32 v209, v95, v95
	v_fmac_f32_e32 v207, v92, v92
	v_fmac_f32_e32 v209, v94, v94
	v_add_f32_e32 v207, v207, v209
	v_mul_f32_e32 v209, v153, v153
	v_mul_f32_e32 v210, v155, v155
	v_fmac_f32_e32 v209, v152, v152
	v_fmac_f32_e32 v210, v154, v154
	v_add_f32_e32 v209, v209, v210
	v_add_f32_e32 v207, v209, v207
	v_mul_f32_e32 v209, v61, v61
	v_mul_f32_e32 v210, v63, v63
	v_fmac_f32_e32 v209, v60, v60
	v_fmac_f32_e32 v210, v62, v62
	v_add_f32_e32 v209, v209, v210
	v_add_f32_e32 v207, v209, v207
	v_mul_f32_e32 v209, v25, v25
	v_mul_f32_e32 v210, v27, v27
	v_fmac_f32_e32 v209, v24, v24
	v_fmac_f32_e32 v210, v26, v26
	v_add_f32_e32 v209, v209, v210
	v_add_f32_e32 v207, v209, v207
	v_mov_b32_e32 v209, v207
	s_nop 1
	v_permlane16_swap_b32_e32 v209, v207
	s_waitcnt lgkmcnt(0)
	v_add_f32_e32 v207, v207, v209
	v_mov_b32_e32 v209, v207
	s_nop 1
	v_permlane32_swap_b32_e32 v209, v207
	s_and_saveexec_b64 s[4:5], s[0:1]
	s_cbranch_execz .LBB0_731
	s_lshl_b32 s6, s38, 10
	s_add_i32 s6, s48, s6
	v_lshl_add_u32 v210, v219, 4, s6
	s_waitcnt lgkmcnt(0)
	v_add_f32_e32 v207, v207, v209
	ds_write_b32 v210, v207 offset:512
.LBB0_731:
	s_or_b64 exec, exec, s[4:5]
	v_mul_f32_e32 v207, v73, v73
	s_waitcnt lgkmcnt(0)
	v_mul_f32_e32 v209, v75, v75
	v_fmac_f32_e32 v207, v72, v72
	v_fmac_f32_e32 v209, v74, v74
	v_add_f32_e32 v207, v207, v209
	v_mul_f32_e32 v209, v149, v149
	v_mul_f32_e32 v210, v151, v151
	v_fmac_f32_e32 v209, v148, v148
	v_fmac_f32_e32 v210, v150, v150
	v_add_f32_e32 v209, v209, v210
	v_add_f32_e32 v207, v209, v207
	v_mul_f32_e32 v209, v57, v57
	v_mul_f32_e32 v210, v59, v59
	v_fmac_f32_e32 v209, v56, v56
	v_fmac_f32_e32 v210, v58, v58
	v_add_f32_e32 v209, v209, v210
	v_add_f32_e32 v207, v209, v207
	v_mul_f32_e32 v209, v21, v21
	v_mul_f32_e32 v210, v23, v23
	v_fmac_f32_e32 v209, v20, v20
	v_fmac_f32_e32 v210, v22, v22
	v_add_f32_e32 v209, v209, v210
	v_add_f32_e32 v207, v209, v207
	v_mov_b32_e32 v209, v207
	s_nop 1
	v_permlane16_swap_b32_e32 v209, v207
	s_waitcnt lgkmcnt(0)
	v_add_f32_e32 v207, v207, v209
	v_mov_b32_e32 v209, v207
	s_nop 1
	v_permlane32_swap_b32_e32 v209, v207
	s_and_saveexec_b64 s[4:5], s[0:1]
	s_cbranch_execz .LBB0_733
	s_lshl_b32 s6, s38, 10
	s_add_i32 s6, s48, s6
	v_lshl_add_u32 v210, v219, 4, s6
	s_waitcnt lgkmcnt(0)
	v_add_f32_e32 v207, v207, v209
	ds_write_b32 v210, v207 offset:768
; __device__ __forceinline__ void panel_rstd(const f32x4 (&v)[2][2][4][2], const Unit& u, int wr, int wc, int fr, int fq, PG8_LAS unsigned char* lds, int wid, int lane,
;                                            float* xslots, unsigned* cnt, unsigned want, float eps) {
;     ...
; #pragma unroll
;     for (int ai = 0; ai < 2; ++ai)
; #pragma unroll
;         for (int m = 0; m < 4; ++m) {
;             float s = 0.f;
; #pragma unroll
;             for (int bj = 0; bj < 2; ++bj)
; #pragma unroll
;                 for (int n = 0; n < 2; ++n) { const f32x4 x = v[ai][bj][m][n]; s += (x[0] * x[0] + x[1] * x[1]) + (x[2] * x[2] + x[3] * x[3]); }
;             s += __shfl_xor(s, 16); s += __shfl_xor(s, 32);
;             if (fq == 0) P[(ai * HALF + wr * 64 + m * 16 + fr) * 4 + wc] = s;
;         }
.LBB0_733:
	s_or_b64 exec, exec, s[4:5]
	v_mul_f32_e32 v207, v81, v81
	s_waitcnt lgkmcnt(0)
	v_mul_f32_e32 v209, v83, v83
	v_fmac_f32_e32 v207, v80, v80
	v_fmac_f32_e32 v209, v82, v82
	v_add_f32_e32 v207, v207, v209
	v_mul_f32_e32 v209, v145, v145
	v_mul_f32_e32 v210, v147, v147
	v_fmac_f32_e32 v209, v144, v144
	v_fmac_f32_e32 v210, v146, v146
	v_add_f32_e32 v209, v209, v210
	v_add_f32_e32 v207, v209, v207
	v_mul_f32_e32 v209, v49, v49
	v_mul_f32_e32 v210, v51, v51
	v_fmac_f32_e32 v209, v48, v48
	v_fmac_f32_e32 v210, v50, v50
	v_add_f32_e32 v209, v209, v210
	v_add_f32_e32 v207, v209, v207
	v_mul_f32_e32 v209, v17, v17
	v_mul_f32_e32 v210, v19, v19
	v_fmac_f32_e32 v209, v16, v16
	v_fmac_f32_e32 v210, v18, v18
	v_add_f32_e32 v209, v209, v210
	v_add_f32_e32 v207, v209, v207
	v_mov_b32_e32 v209, v207
	s_nop 1
	v_permlane16_swap_b32_e32 v209, v207
	s_waitcnt lgkmcnt(0)
	v_add_f32_e32 v207, v207, v209
	v_mov_b32_e32 v209, v207
	s_nop 1
	v_permlane32_swap_b32_e32 v209, v207
	s_and_saveexec_b64 s[4:5], s[0:1]
	s_cbranch_execz .LBB0_735
	s_lshl_b32 s6, s38, 10
	s_add_i32 s6, s48, s6
	v_lshl_add_u32 v210, v219, 4, s6
	s_waitcnt lgkmcnt(0)
	v_add_f32_e32 v207, v207, v209
	ds_write_b32 v210, v207 offset:2048
.LBB0_735:
	s_or_b64 exec, exec, s[4:5]
	v_mul_f32_e32 v207, v65, v65
	s_waitcnt lgkmcnt(0)
	v_mul_f32_e32 v209, v67, v67
	v_fmac_f32_e32 v207, v64, v64
	v_fmac_f32_e32 v209, v66, v66
	v_add_f32_e32 v207, v207, v209
	v_mul_f32_e32 v209, v137, v137
	v_mul_f32_e32 v210, v139, v139
	v_fmac_f32_e32 v209, v136, v136
	v_fmac_f32_e32 v210, v138, v138
	v_add_f32_e32 v209, v209, v210
	v_add_f32_e32 v207, v209, v207
	v_mul_f32_e32 v209, v45, v45
	v_mul_f32_e32 v210, v47, v47
	v_fmac_f32_e32 v209, v44, v44
	v_fmac_f32_e32 v210, v46, v46
	v_add_f32_e32 v209, v209, v210
	v_add_f32_e32 v207, v209, v207
	v_mul_f32_e32 v209, v13, v13
	v_mul_f32_e32 v210, v15, v15
	v_fmac_f32_e32 v209, v12, v12
	v_fmac_f32_e32 v210, v14, v14
	v_add_f32_e32 v209, v209, v210
	v_add_f32_e32 v207, v209, v207
	v_mov_b32_e32 v209, v207
	s_nop 1
	v_permlane16_swap_b32_e32 v209, v207
	s_waitcnt lgkmcnt(0)
	v_add_f32_e32 v207, v207, v209
	v_mov_b32_e32 v209, v207
	s_nop 1
	v_permlane32_swap_b32_e32 v209, v207
	s_and_saveexec_b64 s[4:5], s[0:1]
	s_cbranch_execz .LBB0_737
	s_lshl_b32 s6, s38, 10
	s_add_i32 s6, s48, s6
	v_lshl_add_u32 v210, v219, 4, s6
	s_waitcnt lgkmcnt(0)
	v_add_f32_e32 v207, v207, v209
	ds_write_b32 v210, v207 offset:2304
.LBB0_737:
	s_or_b64 exec, exec, s[4:5]
	v_mul_f32_e32 v207, v69, v69
	s_waitcnt lgkmcnt(0)
	v_mul_f32_e32 v209, v71, v71
	v_fmac_f32_e32 v207, v68, v68
	v_fmac_f32_e32 v209, v70, v70
	v_add_f32_e32 v207, v207, v209
	v_mul_f32_e32 v209, v117, v117
	v_mul_f32_e32 v210, v119, v119
	v_fmac_f32_e32 v209, v116, v116
	v_fmac_f32_e32 v210, v118, v118
	v_add_f32_e32 v209, v209, v210
	v_add_f32_e32 v207, v209, v207
	v_mul_f32_e32 v209, v41, v41
	v_mul_f32_e32 v210, v43, v43
	v_fmac_f32_e32 v209, v40, v40
	v_fmac_f32_e32 v210, v42, v42
	v_add_f32_e32 v209, v209, v210
	v_add_f32_e32 v207, v209, v207
	v_mul_f32_e32 v209, v9, v9
	v_mul_f32_e32 v210, v11, v11
	v_fmac_f32_e32 v209, v8, v8
	v_fmac_f32_e32 v210, v10, v10
	v_add_f32_e32 v209, v209, v210
	v_add_f32_e32 v207, v209, v207
	v_mov_b32_e32 v209, v207
	s_nop 1
	v_permlane16_swap_b32_e32 v209, v207
	s_waitcnt lgkmcnt(0)
	v_add_f32_e32 v207, v207, v209
	v_mov_b32_e32 v209, v207
	s_nop 1
	v_permlane32_swap_b32_e32 v209, v207
	s_and_saveexec_b64 s[4:5], s[0:1]
	s_cbranch_execz .LBB0_739
	s_lshl_b32 s6, s38, 10
	s_add_i32 s6, s48, s6
	v_lshl_add_u32 v210, v219, 4, s6
	s_waitcnt lgkmcnt(0)
	v_add_f32_e32 v207, v207, v209
	ds_write_b32 v210, v207 offset:2560
.LBB0_739:
	s_or_b64 exec, exec, s[4:5]
	v_mul_f32_e32 v207, v53, v53
	s_waitcnt lgkmcnt(0)
	v_mul_f32_e32 v209, v55, v55
	v_fmac_f32_e32 v207, v52, v52
	v_fmac_f32_e32 v209, v54, v54
	v_add_f32_e32 v207, v207, v209
	v_mul_f32_e32 v209, v113, v113
	v_mul_f32_e32 v210, v115, v115
	v_fmac_f32_e32 v209, v112, v112
	v_fmac_f32_e32 v210, v114, v114
	v_add_f32_e32 v209, v209, v210
	v_add_f32_e32 v207, v209, v207
	v_mul_f32_e32 v209, v37, v37
	v_mul_f32_e32 v210, v39, v39
	v_fmac_f32_e32 v209, v36, v36
	v_fmac_f32_e32 v210, v38, v38
	v_add_f32_e32 v209, v209, v210
	v_add_f32_e32 v207, v209, v207
	v_mul_f32_e32 v209, v5, v5
	v_mul_f32_e32 v210, v7, v7
	v_fmac_f32_e32 v209, v4, v4
	v_fmac_f32_e32 v210, v6, v6
	v_add_f32_e32 v209, v209, v210
	v_add_f32_e32 v207, v209, v207
	v_mov_b32_e32 v209, v207
	s_nop 1
	v_permlane16_swap_b32_e32 v209, v207
	s_waitcnt lgkmcnt(0)
	v_add_f32_e32 v207, v207, v209
	v_mov_b32_e32 v209, v207
	s_nop 1
	v_permlane32_swap_b32_e32 v209, v207
	s_and_saveexec_b64 s[4:5], s[0:1]
	s_cbranch_execz .LBB0_741
	s_lshl_b32 s6, s38, 10
	s_add_i32 s6, s48, s6
	v_lshl_add_u32 v210, v219, 4, s6
	s_waitcnt lgkmcnt(0)
	v_add_f32_e32 v207, v207, v209
	ds_write_b32 v210, v207 offset:2816

; __device__ __forceinline__ float f16lo(unsigned w) { return (float)__builtin_bit_cast(f16x2, w)[0]; }
; __device__ __forceinline__ float f16hi(unsigned w) { return (float)__builtin_bit_cast(f16x2, w)[1]; }
;     __device__ __forceinline__ void fused(f32x4 (&acc)[2][2][4][2], const Unit& u, int wr, int wc, int fr, int fq, PG8_LAS unsigned char* lds, int wid, int lane) const {
;     ...
;         for (int bj = 0; bj < 2; ++bj)
; #pragma unroll
;             for (int n = 0; n < 2; ++n) {
;                 const int c = col0 + bj * HALF + n * 4;
;                 const f32x4 gg = *(const f32x4*)(gate + (size_t)b * 9216 + c) * *(const f32x4*)(gpost + c) * res_w;
; #pragma unroll
;                 for (int ai = 0; ai < 2; ++ai)
; #pragma unroll
;                     for (int m = 0; m < 4; ++m) { const int r = ai * HALF + wr * 64 + m * 16 + fr;
;                         const unsigned w0 = n ? pre[ai][m][bj].z : pre[ai][m][bj].x, w1 = n ? pre[ai][m][bj].w : pre[ai][m][bj].y;
;                         const f32x4 xv = {f16lo(w0), f16hi(w0), f16lo(w1), f16hi(w1)};
;                         acc[ai][bj][m][n] = xv + gg * (acc[ai][bj][m][n] * S[r]); }
.LBB0_753:
	s_or_b64 exec, exec, s[34:35]
	s_ashr_i32 s8, s39, 31
	s_lshr_b32 s8, s8, 27
	s_add_i32 s8, s39, s8
	s_ashr_i32 s8, s8, 5
	s_mul_i32 s35, s8, 0x9000
	s_mul_hi_i32 s34, s8, 0x9000
	s_add_u32 s8, s30, s35
	s_addc_u32 s9, s31, s34
	s_waitcnt lgkmcnt(0)
	v_lshlrev_b64 v[208:209], 2, v[0:1]
	s_waitcnt lgkmcnt(0)
	s_barrier
	v_lshl_add_u64 v[210:211], s[8:9], 0, v[208:209]
	v_lshl_add_u64 v[212:213], s[28:29], 0, v[208:209]
	flat_load_dwordx4 v[214:217], v[210:211]
	flat_load_dwordx4 v[236:239], v[212:213]
	s_and_b32 s11, s17, 0xffffff00
	s_add_i32 s11, s11, 0
	v_lshl_add_u32 v227, v219, 2, s11
	s_cmp_lg_u64 s[12:13], 0
	s_cselect_b64 s[8:9], -1, 0
	s_cmp_eq_u64 s[12:13], 0
	s_waitcnt vmcnt(0) lgkmcnt(0)
	v_pk_mul_f32 v[216:217], v[216:217], v[238:239]
	v_pk_mul_f32 v[236:237], v[214:215], v[236:237]
	v_pk_mul_f32 v[214:215], s[16:17], v[216:217] op_sel_hi:[0,1]
	v_pk_mul_f32 v[216:217], s[16:17], v[236:237] op_sel_hi:[0,1]
	v_cvt_f32_f16_sdwa v237, v192 dst_sel:DWORD dst_unused:UNUSED_PAD src0_sel:WORD_1
	v_cvt_f32_f16_e32 v236, v192
	v_add_u32_e32 v192, 0x1000, v227
	ds_read2_b32 v[240:241], v192 offset1:16
	v_cvt_f32_f16_sdwa v239, v193 dst_sel:DWORD dst_unused:UNUSED_PAD src0_sel:WORD_1
	v_cvt_f32_f16_e32 v238, v193
	s_waitcnt lgkmcnt(0)
	v_pk_mul_f32 v[96:97], v[96:97], v[240:241] op_sel_hi:[1,0]
	s_nop 0
	v_pk_fma_f32 v[96:97], v[216:217], v[96:97], v[236:237]
	v_cvt_f32_f16_sdwa v237, v188 dst_sel:DWORD dst_unused:UNUSED_PAD src0_sel:WORD_1
	v_cvt_f32_f16_e32 v236, v188
	v_mov_b32_e32 v188, v241
	v_pk_mul_f32 v[98:99], v[98:99], v[240:241] op_sel_hi:[1,0]
	v_pk_mul_f32 v[88:89], v[88:89], v[188:189] op_sel_hi:[1,0]
	v_pk_fma_f32 v[98:99], v[214:215], v[98:99], v[238:239]
	v_cvt_f32_f16_sdwa v239, v189 dst_sel:DWORD dst_unused:UNUSED_PAD src0_sel:WORD_1
	v_cvt_f32_f16_e32 v238, v189
	v_pk_mul_f32 v[90:91], v[90:91], v[188:189] op_sel_hi:[1,0]
	v_pk_fma_f32 v[88:89], v[216:217], v[88:89], v[236:237]
	v_cvt_f32_f16_sdwa v189, v184 dst_sel:DWORD dst_unused:UNUSED_PAD src0_sel:WORD_1
	v_cvt_f32_f16_e32 v188, v184
	v_cvt_f32_f16_sdwa v237, v185 dst_sel:DWORD dst_unused:UNUSED_PAD src0_sel:WORD_1
	v_cvt_f32_f16_e32 v236, v185
	ds_read2_b32 v[184:185], v192 offset0:32 offset1:48
	v_pk_fma_f32 v[90:91], v[214:215], v[90:91], v[238:239]
	s_waitcnt lgkmcnt(0)
	v_pk_mul_f32 v[92:93], v[92:93], v[184:185] op_sel_hi:[1,0]
	v_pk_mul_f32 v[94:95], v[94:95], v[184:185] op_sel_hi:[1,0]
	v_pk_fma_f32 v[92:93], v[216:217], v[92:93], v[188:189]
	v_cvt_f32_f16_sdwa v189, v180 dst_sel:DWORD dst_unused:UNUSED_PAD src0_sel:WORD_1
	v_cvt_f32_f16_e32 v188, v180
	v_mov_b32_e32 v180, v185
	v_pk_fma_f32 v[94:95], v[214:215], v[94:95], v[236:237]
	v_cvt_f32_f16_sdwa v237, v181 dst_sel:DWORD dst_unused:UNUSED_PAD src0_sel:WORD_1
	v_cvt_f32_f16_e32 v236, v181
	v_pk_mul_f32 v[74:75], v[74:75], v[180:181] op_sel_hi:[1,0]
	v_pk_mul_f32 v[72:73], v[72:73], v[180:181] op_sel_hi:[1,0]
	v_cvt_f32_f16_sdwa v181, v176 dst_sel:DWORD dst_unused:UNUSED_PAD src0_sel:WORD_1
	v_cvt_f32_f16_e32 v180, v176
	v_cvt_f32_f16_sdwa v185, v177 dst_sel:DWORD dst_unused:UNUSED_PAD src0_sel:WORD_1
	v_cvt_f32_f16_e32 v184, v177
	ds_read2_b32 v[176:177], v192 offset0:128 offset1:144
	v_pk_fma_f32 v[74:75], v[214:215], v[74:75], v[236:237]
	v_pk_fma_f32 v[72:73], v[216:217], v[72:73], v[188:189]
	s_waitcnt lgkmcnt(0)
	v_pk_mul_f32 v[80:81], v[80:81], v[176:177] op_sel_hi:[1,0]
	v_pk_mul_f32 v[82:83], v[82:83], v[176:177] op_sel_hi:[1,0]
	v_pk_fma_f32 v[80:81], v[216:217], v[80:81], v[180:181]
	v_cvt_f32_f16_sdwa v181, v172 dst_sel:DWORD dst_unused:UNUSED_PAD src0_sel:WORD_1
	v_cvt_f32_f16_e32 v180, v172
	v_mov_b32_e32 v172, v177
	v_pk_fma_f32 v[82:83], v[214:215], v[82:83], v[184:185]
	v_cvt_f32_f16_sdwa v185, v173 dst_sel:DWORD dst_unused:UNUSED_PAD src0_sel:WORD_1
	v_cvt_f32_f16_e32 v184, v173
	v_pk_mul_f32 v[66:67], v[66:67], v[172:173] op_sel_hi:[1,0]
	v_pk_mul_f32 v[64:65], v[64:65], v[172:173] op_sel_hi:[1,0]
	v_cvt_f32_f16_sdwa v173, v168 dst_sel:DWORD dst_unused:UNUSED_PAD src0_sel:WORD_1
	v_cvt_f32_f16_e32 v172, v168
	v_cvt_f32_f16_sdwa v177, v169 dst_sel:DWORD dst_unused:UNUSED_PAD src0_sel:WORD_1
	v_cvt_f32_f16_e32 v176, v169
	ds_read2_b32 v[168:169], v192 offset0:160 offset1:176
	v_pk_fma_f32 v[66:67], v[214:215], v[66:67], v[184:185]
	v_pk_fma_f32 v[64:65], v[216:217], v[64:65], v[180:181]
	s_waitcnt lgkmcnt(0)
	v_pk_mul_f32 v[70:71], v[70:71], v[168:169] op_sel_hi:[1,0]
	v_pk_mul_f32 v[68:69], v[68:69], v[168:169] op_sel_hi:[1,0]
	v_pk_fma_f32 v[70:71], v[214:215], v[70:71], v[176:177]
	v_pk_fma_f32 v[68:69], v[216:217], v[68:69], v[172:173]
	v_cvt_f32_f16_sdwa v173, v164 dst_sel:DWORD dst_unused:UNUSED_PAD src0_sel:WORD_1
	v_cvt_f32_f16_e32 v172, v164
	v_cvt_f32_f16_sdwa v177, v165 dst_sel:DWORD dst_unused:UNUSED_PAD src0_sel:WORD_1
	v_cvt_f32_f16_e32 v176, v165
	v_mov_b32_e32 v164, v169
	v_pk_mul_f32 v[54:55], v[54:55], v[164:165] op_sel_hi:[1,0]
	v_pk_mul_f32 v[52:53], v[52:53], v[164:165] op_sel_hi:[1,0]
	v_pk_fma_f32 v[54:55], v[214:215], v[54:55], v[176:177]
	v_pk_fma_f32 v[52:53], v[216:217], v[52:53], v[172:173]
	flat_load_dwordx4 v[214:217], v[210:211] offset:16
	flat_load_dwordx4 v[236:239], v[212:213] offset:16
	ds_read2_b32 v[180:181], v192 offset1:16
	v_cvt_f32_f16_sdwa v173, v194 dst_sel:DWORD dst_unused:UNUSED_PAD src0_sel:WORD_1
	v_cvt_f32_f16_e32 v172, v194
	v_cvt_f32_f16_sdwa v177, v195 dst_sel:DWORD dst_unused:UNUSED_PAD src0_sel:WORD_1
	v_cvt_f32_f16_e32 v176, v195
	s_waitcnt lgkmcnt(0)
; __device__ __forceinline__ float f16lo(unsigned w) { return (float)__builtin_bit_cast(f16x2, w)[0]; }
; __device__ __forceinline__ float f16hi(unsigned w) { return (float)__builtin_bit_cast(f16x2, w)[1]; }
;     __device__ __forceinline__ void fused(f32x4 (&acc)[2][2][4][2], const Unit& u, int wr, int wc, int fr, int fq, PG8_LAS unsigned char* lds, int wid, int lane) const {
;     ...
;         for (int bj = 0; bj < 2; ++bj)
; #pragma unroll
;             for (int n = 0; n < 2; ++n) {
;                 const int c = col0 + bj * HALF + n * 4;
;                 const f32x4 gg = *(const f32x4*)(gate + (size_t)b * 9216 + c) * *(const f32x4*)(gpost + c) * res_w;
; #pragma unroll
;                 for (int ai = 0; ai < 2; ++ai)
; #pragma unroll
;                     for (int m = 0; m < 4; ++m) { const int r = ai * HALF + wr * 64 + m * 16 + fr;
;                         const unsigned w0 = n ? pre[ai][m][bj].z : pre[ai][m][bj].x, w1 = n ? pre[ai][m][bj].w : pre[ai][m][bj].y;
;                         const f32x4 xv = {f16lo(w0), f16hi(w0), f16lo(w1), f16hi(w1)};
;                         acc[ai][bj][m][n] = xv + gg * (acc[ai][bj][m][n] * S[r]); }
;                 asm volatile("" ::: "memory");
;             }
	v_pk_mul_f32 v[162:163], v[162:163], v[180:181] op_sel_hi:[1,0]
	v_pk_mul_f32 v[160:161], v[160:161], v[180:181] op_sel_hi:[1,0]
	v_mov_b32_e32 v180, v181
	v_pk_mul_f32 v[158:159], v[158:159], v[180:181] op_sel_hi:[1,0]
	v_pk_mul_f32 v[156:157], v[156:157], v[180:181] op_sel_hi:[1,0]
	ds_read2_b32 v[180:181], v192 offset0:32 offset1:48
	s_waitcnt lgkmcnt(0)
	v_pk_mul_f32 v[154:155], v[154:155], v[180:181] op_sel_hi:[1,0]
	v_pk_mul_f32 v[152:153], v[152:153], v[180:181] op_sel_hi:[1,0]
	v_mov_b32_e32 v180, v181
	v_pk_mul_f32 v[150:151], v[150:151], v[180:181] op_sel_hi:[1,0]
	v_pk_mul_f32 v[148:149], v[148:149], v[180:181] op_sel_hi:[1,0]
	s_waitcnt vmcnt(0)
	v_pk_mul_f32 v[164:165], v[216:217], v[238:239]
	v_pk_mul_f32 v[168:169], v[214:215], v[236:237]
	v_pk_mul_f32 v[164:165], s[16:17], v[164:165] op_sel_hi:[0,1]
	v_pk_mul_f32 v[168:169], s[16:17], v[168:169] op_sel_hi:[0,1]
	v_pk_fma_f32 v[162:163], v[164:165], v[162:163], v[176:177]
	v_pk_fma_f32 v[160:161], v[168:169], v[160:161], v[172:173]
	v_cvt_f32_f16_sdwa v173, v190 dst_sel:DWORD dst_unused:UNUSED_PAD src0_sel:WORD_1
	v_cvt_f32_f16_e32 v172, v190
	v_cvt_f32_f16_sdwa v177, v191 dst_sel:DWORD dst_unused:UNUSED_PAD src0_sel:WORD_1
	v_cvt_f32_f16_e32 v176, v191
	v_pk_fma_f32 v[156:157], v[168:169], v[156:157], v[172:173]
	v_cvt_f32_f16_sdwa v173, v186 dst_sel:DWORD dst_unused:UNUSED_PAD src0_sel:WORD_1
	v_pk_fma_f32 v[158:159], v[164:165], v[158:159], v[176:177]
	v_cvt_f32_f16_e32 v172, v186
	v_cvt_f32_f16_sdwa v177, v187 dst_sel:DWORD dst_unused:UNUSED_PAD src0_sel:WORD_1
	v_cvt_f32_f16_e32 v176, v187
	v_pk_fma_f32 v[152:153], v[168:169], v[152:153], v[172:173]
	v_cvt_f32_f16_sdwa v173, v182 dst_sel:DWORD dst_unused:UNUSED_PAD src0_sel:WORD_1
	v_pk_fma_f32 v[154:155], v[164:165], v[154:155], v[176:177]
	v_cvt_f32_f16_e32 v172, v182
	v_cvt_f32_f16_sdwa v177, v183 dst_sel:DWORD dst_unused:UNUSED_PAD src0_sel:WORD_1
	v_cvt_f32_f16_e32 v176, v183
	v_pk_fma_f32 v[148:149], v[168:169], v[148:149], v[172:173]
	v_cvt_f32_f16_sdwa v173, v178 dst_sel:DWORD dst_unused:UNUSED_PAD src0_sel:WORD_1
	v_pk_fma_f32 v[150:151], v[164:165], v[150:151], v[176:177]
	v_cvt_f32_f16_e32 v172, v178
	v_cvt_f32_f16_sdwa v177, v179 dst_sel:DWORD dst_unused:UNUSED_PAD src0_sel:WORD_1
	v_cvt_f32_f16_e32 v176, v179
	ds_read2_b32 v[178:179], v192 offset0:128 offset1:144
	s_waitcnt lgkmcnt(0)
	v_pk_mul_f32 v[144:145], v[144:145], v[178:179] op_sel_hi:[1,0]
	s_nop 0
	v_pk_fma_f32 v[144:145], v[168:169], v[144:145], v[172:173]
	v_cvt_f32_f16_sdwa v173, v174 dst_sel:DWORD dst_unused:UNUSED_PAD src0_sel:WORD_1
	v_cvt_f32_f16_e32 v172, v174
	v_mov_b32_e32 v174, v179
	v_pk_mul_f32 v[146:147], v[146:147], v[178:179] op_sel_hi:[1,0]
	v_pk_mul_f32 v[136:137], v[136:137], v[174:175] op_sel_hi:[1,0]
	v_pk_fma_f32 v[146:147], v[164:165], v[146:147], v[176:177]
	v_cvt_f32_f16_sdwa v177, v175 dst_sel:DWORD dst_unused:UNUSED_PAD src0_sel:WORD_1
	v_cvt_f32_f16_e32 v176, v175
	v_pk_mul_f32 v[138:139], v[138:139], v[174:175] op_sel_hi:[1,0]
	v_pk_fma_f32 v[136:137], v[168:169], v[136:137], v[172:173]
	v_cvt_f32_f16_sdwa v173, v170 dst_sel:DWORD dst_unused:UNUSED_PAD src0_sel:WORD_1
	v_cvt_f32_f16_e32 v172, v170
	v_cvt_f32_f16_sdwa v175, v171 dst_sel:DWORD dst_unused:UNUSED_PAD src0_sel:WORD_1
	v_cvt_f32_f16_e32 v174, v171
	ds_read2_b32 v[170:171], v192 offset0:160 offset1:176
	v_pk_fma_f32 v[138:139], v[164:165], v[138:139], v[176:177]
	s_waitcnt lgkmcnt(0)
	v_pk_mul_f32 v[118:119], v[118:119], v[170:171] op_sel_hi:[1,0]
	v_pk_mul_f32 v[116:117], v[116:117], v[170:171] op_sel_hi:[1,0]
	v_pk_fma_f32 v[118:119], v[164:165], v[118:119], v[174:175]
	v_pk_fma_f32 v[116:117], v[168:169], v[116:117], v[172:173]
	v_cvt_f32_f16_sdwa v173, v166 dst_sel:DWORD dst_unused:UNUSED_PAD src0_sel:WORD_1
	v_cvt_f32_f16_e32 v172, v166
	v_cvt_f32_f16_sdwa v175, v167 dst_sel:DWORD dst_unused:UNUSED_PAD src0_sel:WORD_1
	v_cvt_f32_f16_e32 v174, v167
	v_mov_b32_e32 v166, v171
	v_pk_mul_f32 v[114:115], v[114:115], v[166:167] op_sel_hi:[1,0]
	v_pk_mul_f32 v[112:113], v[112:113], v[166:167] op_sel_hi:[1,0]
	v_pk_fma_f32 v[114:115], v[164:165], v[114:115], v[174:175]
	v_pk_fma_f32 v[112:113], v[168:169], v[112:113], v[172:173]
	flat_load_dwordx4 v[164:167], v[210:211] offset:512
	flat_load_dwordx4 v[168:171], v[212:213] offset:512
	s_waitcnt vmcnt(0) lgkmcnt(0)
	v_pk_mul_f32 v[166:167], v[166:167], v[170:171]
	v_pk_mul_f32 v[168:169], v[164:165], v[168:169]
	v_pk_mul_f32 v[164:165], s[16:17], v[166:167] op_sel_hi:[0,1]
	v_pk_mul_f32 v[166:167], s[16:17], v[168:169] op_sel_hi:[0,1]
	v_cvt_f32_f16_sdwa v169, v140 dst_sel:DWORD dst_unused:UNUSED_PAD src0_sel:WORD_1
	v_cvt_f32_f16_e32 v168, v140
	v_cvt_f32_f16_sdwa v171, v141 dst_sel:DWORD dst_unused:UNUSED_PAD src0_sel:WORD_1
	v_cvt_f32_f16_e32 v170, v141
	ds_read2_b32 v[140:141], v192 offset1:16
	s_waitcnt lgkmcnt(0)
	v_pk_mul_f32 v[84:85], v[84:85], v[140:141] op_sel_hi:[1,0]
	v_pk_mul_f32 v[86:87], v[86:87], v[140:141] op_sel_hi:[1,0]
	v_pk_fma_f32 v[84:85], v[166:167], v[84:85], v[168:169]
	v_cvt_f32_f16_sdwa v169, v132 dst_sel:DWORD dst_unused:UNUSED_PAD src0_sel:WORD_1
	v_cvt_f32_f16_e32 v168, v132
	v_mov_b32_e32 v132, v141
	v_pk_fma_f32 v[86:87], v[164:165], v[86:87], v[170:171]
	v_cvt_f32_f16_sdwa v171, v133 dst_sel:DWORD dst_unused:UNUSED_PAD src0_sel:WORD_1
	v_cvt_f32_f16_e32 v170, v133
	v_pk_mul_f32 v[78:79], v[78:79], v[132:133] op_sel_hi:[1,0]
	v_pk_mul_f32 v[76:77], v[76:77], v[132:133] op_sel_hi:[1,0]
	v_cvt_f32_f16_sdwa v133, v128 dst_sel:DWORD dst_unused:UNUSED_PAD src0_sel:WORD_1
	v_cvt_f32_f16_e32 v132, v128
	v_cvt_f32_f16_sdwa v141, v129 dst_sel:DWORD dst_unused:UNUSED_PAD src0_sel:WORD_1
	v_cvt_f32_f16_e32 v140, v129
	ds_read2_b32 v[128:129], v192 offset0:32 offset1:48
	v_pk_fma_f32 v[78:79], v[164:165], v[78:79], v[170:171]
	v_pk_fma_f32 v[76:77], v[166:167], v[76:77], v[168:169]
	s_waitcnt lgkmcnt(0)
; __device__ __forceinline__ float f16lo(unsigned w) { return (float)__builtin_bit_cast(f16x2, w)[0]; }
; __device__ __forceinline__ float f16hi(unsigned w) { return (float)__builtin_bit_cast(f16x2, w)[1]; }
;     __device__ __forceinline__ void fused(f32x4 (&acc)[2][2][4][2], const Unit& u, int wr, int wc, int fr, int fq, PG8_LAS unsigned char* lds, int wid, int lane) const {
;     ...
;         for (int bj = 0; bj < 2; ++bj)
; #pragma unroll
;             for (int n = 0; n < 2; ++n) {
;                 const int c = col0 + bj * HALF + n * 4;
;                 const f32x4 gg = *(const f32x4*)(gate + (size_t)b * 9216 + c) * *(const f32x4*)(gpost + c) * res_w;
; #pragma unroll
;                 for (int ai = 0; ai < 2; ++ai)
; #pragma unroll
;                     for (int m = 0; m < 4; ++m) { const int r = ai * HALF + wr * 64 + m * 16 + fr;
;                         const unsigned w0 = n ? pre[ai][m][bj].z : pre[ai][m][bj].x, w1 = n ? pre[ai][m][bj].w : pre[ai][m][bj].y;
;                         const f32x4 xv = {f16lo(w0), f16hi(w0), f16lo(w1), f16hi(w1)};
;                         acc[ai][bj][m][n] = xv + gg * (acc[ai][bj][m][n] * S[r]); }
;                 asm volatile("" ::: "memory");
;             }
	v_pk_mul_f32 v[60:61], v[60:61], v[128:129] op_sel_hi:[1,0]
	v_pk_mul_f32 v[62:63], v[62:63], v[128:129] op_sel_hi:[1,0]
	v_pk_fma_f32 v[60:61], v[166:167], v[60:61], v[132:133]
	v_cvt_f32_f16_sdwa v133, v124 dst_sel:DWORD dst_unused:UNUSED_PAD src0_sel:WORD_1
	v_cvt_f32_f16_e32 v132, v124
	v_mov_b32_e32 v124, v129
	v_pk_fma_f32 v[62:63], v[164:165], v[62:63], v[140:141]
	v_cvt_f32_f16_sdwa v141, v125 dst_sel:DWORD dst_unused:UNUSED_PAD src0_sel:WORD_1
	v_cvt_f32_f16_e32 v140, v125
	v_pk_mul_f32 v[58:59], v[58:59], v[124:125] op_sel_hi:[1,0]
	v_pk_mul_f32 v[56:57], v[56:57], v[124:125] op_sel_hi:[1,0]
	v_cvt_f32_f16_sdwa v125, v120 dst_sel:DWORD dst_unused:UNUSED_PAD src0_sel:WORD_1
	v_cvt_f32_f16_e32 v124, v120
	v_cvt_f32_f16_sdwa v129, v121 dst_sel:DWORD dst_unused:UNUSED_PAD src0_sel:WORD_1
	v_cvt_f32_f16_e32 v128, v121
	ds_read2_b32 v[120:121], v192 offset0:128 offset1:144
	v_pk_fma_f32 v[58:59], v[164:165], v[58:59], v[140:141]
	v_pk_fma_f32 v[56:57], v[166:167], v[56:57], v[132:133]
	s_waitcnt lgkmcnt(0)
	v_pk_mul_f32 v[48:49], v[48:49], v[120:121] op_sel_hi:[1,0]
	v_pk_mul_f32 v[50:51], v[50:51], v[120:121] op_sel_hi:[1,0]
	v_pk_fma_f32 v[48:49], v[166:167], v[48:49], v[124:125]
	v_cvt_f32_f16_sdwa v125, v108 dst_sel:DWORD dst_unused:UNUSED_PAD src0_sel:WORD_1
	v_cvt_f32_f16_e32 v124, v108
	v_mov_b32_e32 v108, v121
	v_pk_fma_f32 v[50:51], v[164:165], v[50:51], v[128:129]
	v_cvt_f32_f16_sdwa v129, v109 dst_sel:DWORD dst_unused:UNUSED_PAD src0_sel:WORD_1
	v_cvt_f32_f16_e32 v128, v109
	v_pk_mul_f32 v[46:47], v[46:47], v[108:109] op_sel_hi:[1,0]
	v_pk_mul_f32 v[44:45], v[44:45], v[108:109] op_sel_hi:[1,0]
	v_cvt_f32_f16_sdwa v109, v104 dst_sel:DWORD dst_unused:UNUSED_PAD src0_sel:WORD_1
	v_cvt_f32_f16_e32 v108, v104
	v_cvt_f32_f16_sdwa v121, v105 dst_sel:DWORD dst_unused:UNUSED_PAD src0_sel:WORD_1
	v_cvt_f32_f16_e32 v120, v105
	ds_read2_b32 v[104:105], v192 offset0:160 offset1:176
	v_pk_fma_f32 v[46:47], v[164:165], v[46:47], v[128:129]
	v_pk_fma_f32 v[44:45], v[166:167], v[44:45], v[124:125]
	s_waitcnt lgkmcnt(0)
	v_pk_mul_f32 v[42:43], v[42:43], v[104:105] op_sel_hi:[1,0]
	v_pk_mul_f32 v[40:41], v[40:41], v[104:105] op_sel_hi:[1,0]
	v_pk_fma_f32 v[42:43], v[164:165], v[42:43], v[120:121]
	v_pk_fma_f32 v[40:41], v[166:167], v[40:41], v[108:109]
	v_cvt_f32_f16_sdwa v109, v100 dst_sel:DWORD dst_unused:UNUSED_PAD src0_sel:WORD_1
	v_cvt_f32_f16_e32 v108, v100
	v_cvt_f32_f16_sdwa v121, v101 dst_sel:DWORD dst_unused:UNUSED_PAD src0_sel:WORD_1
	v_cvt_f32_f16_e32 v120, v101
	v_mov_b32_e32 v100, v105
	v_pk_mul_f32 v[38:39], v[38:39], v[100:101] op_sel_hi:[1,0]
	v_pk_mul_f32 v[36:37], v[36:37], v[100:101] op_sel_hi:[1,0]
	v_pk_fma_f32 v[38:39], v[164:165], v[38:39], v[120:121]
	v_pk_fma_f32 v[36:37], v[166:167], v[36:37], v[108:109]
	flat_load_dwordx4 v[164:167], v[210:211] offset:528
	flat_load_dwordx4 v[168:171], v[212:213] offset:528
	ds_read2_b32 v[124:125], v192 offset1:16
	v_cvt_f32_f16_sdwa v109, v142 dst_sel:DWORD dst_unused:UNUSED_PAD src0_sel:WORD_1
	v_cvt_f32_f16_e32 v108, v142
	v_cvt_f32_f16_sdwa v121, v143 dst_sel:DWORD dst_unused:UNUSED_PAD src0_sel:WORD_1
	v_cvt_f32_f16_e32 v120, v143
	s_waitcnt lgkmcnt(0)
	v_pk_mul_f32 v[34:35], v[34:35], v[124:125] op_sel_hi:[1,0]
	v_pk_mul_f32 v[32:33], v[32:33], v[124:125] op_sel_hi:[1,0]
	v_mov_b32_e32 v124, v125
	v_pk_mul_f32 v[30:31], v[30:31], v[124:125] op_sel_hi:[1,0]
	v_pk_mul_f32 v[28:29], v[28:29], v[124:125] op_sel_hi:[1,0]
	ds_read2_b32 v[124:125], v192 offset0:32 offset1:48
	s_waitcnt lgkmcnt(0)
	v_pk_mul_f32 v[26:27], v[26:27], v[124:125] op_sel_hi:[1,0]
	v_pk_mul_f32 v[24:25], v[24:25], v[124:125] op_sel_hi:[1,0]
	v_mov_b32_e32 v124, v125
	v_pk_mul_f32 v[22:23], v[22:23], v[124:125] op_sel_hi:[1,0]
	v_pk_mul_f32 v[20:21], v[20:21], v[124:125] op_sel_hi:[1,0]
	s_waitcnt vmcnt(0)
	v_pk_mul_f32 v[100:101], v[166:167], v[170:171]
	v_pk_mul_f32 v[104:105], v[164:165], v[168:169]
	v_pk_mul_f32 v[100:101], s[16:17], v[100:101] op_sel_hi:[0,1]
	v_pk_mul_f32 v[104:105], s[16:17], v[104:105] op_sel_hi:[0,1]
	v_pk_fma_f32 v[34:35], v[100:101], v[34:35], v[120:121]
	v_pk_fma_f32 v[32:33], v[104:105], v[32:33], v[108:109]
	v_cvt_f32_f16_sdwa v109, v134 dst_sel:DWORD dst_unused:UNUSED_PAD src0_sel:WORD_1
	v_cvt_f32_f16_e32 v108, v134
	v_cvt_f32_f16_sdwa v121, v135 dst_sel:DWORD dst_unused:UNUSED_PAD src0_sel:WORD_1
	v_cvt_f32_f16_e32 v120, v135
	v_pk_fma_f32 v[28:29], v[104:105], v[28:29], v[108:109]
	v_cvt_f32_f16_sdwa v109, v130 dst_sel:DWORD dst_unused:UNUSED_PAD src0_sel:WORD_1
	v_pk_fma_f32 v[30:31], v[100:101], v[30:31], v[120:121]
	v_cvt_f32_f16_e32 v108, v130
	v_cvt_f32_f16_sdwa v121, v131 dst_sel:DWORD dst_unused:UNUSED_PAD src0_sel:WORD_1
	v_cvt_f32_f16_e32 v120, v131
	v_pk_fma_f32 v[24:25], v[104:105], v[24:25], v[108:109]
	v_cvt_f32_f16_sdwa v109, v126 dst_sel:DWORD dst_unused:UNUSED_PAD src0_sel:WORD_1
	v_pk_fma_f32 v[26:27], v[100:101], v[26:27], v[120:121]
	v_cvt_f32_f16_e32 v108, v126
	v_cvt_f32_f16_sdwa v121, v127 dst_sel:DWORD dst_unused:UNUSED_PAD src0_sel:WORD_1
	v_cvt_f32_f16_e32 v120, v127
	v_pk_fma_f32 v[20:21], v[104:105], v[20:21], v[108:109]
	v_cvt_f32_f16_sdwa v109, v122 dst_sel:DWORD dst_unused:UNUSED_PAD src0_sel:WORD_1
	v_pk_fma_f32 v[22:23], v[100:101], v[22:23], v[120:121]
	v_cvt_f32_f16_e32 v108, v122
	v_cvt_f32_f16_sdwa v121, v123 dst_sel:DWORD dst_unused:UNUSED_PAD src0_sel:WORD_1
	v_cvt_f32_f16_e32 v120, v123
	ds_read2_b32 v[122:123], v192 offset0:128 offset1:144
	s_waitcnt lgkmcnt(0)
; __device__ __forceinline__ float f16lo(unsigned w) { return (float)__builtin_bit_cast(f16x2, w)[0]; }
; __device__ __forceinline__ float f16hi(unsigned w) { return (float)__builtin_bit_cast(f16x2, w)[1]; }
; __device__ __forceinline__ void panel_rstd(const f32x4 (&v)[2][2][4][2], const Unit& u, int wr, int wc, int fr, int fq, PG8_LAS unsigned char* lds, int wid, int lane,
;                                            float* xslots, unsigned* cnt, unsigned want, float eps) {
;     ...
; #pragma unroll
;     for (int ai = 0; ai < 2; ++ai)
; #pragma unroll
;         for (int m = 0; m < 4; ++m) {
;             float s = 0.f;
; #pragma unroll
;             for (int bj = 0; bj < 2; ++bj)
; #pragma unroll
;                 for (int n = 0; n < 2; ++n) { const f32x4 x = v[ai][bj][m][n]; s += (x[0] * x[0] + x[1] * x[1]) + (x[2] * x[2] + x[3] * x[3]); }
;             s += __shfl_xor(s, 16); s += __shfl_xor(s, 32);
;             if (fq == 0) P[(ai * HALF + wr * 64 + m * 16 + fr) * 4 + wc] = s;
;     __device__ __forceinline__ void fused(f32x4 (&acc)[2][2][4][2], const Unit& u, int wr, int wc, int fr, int fq, PG8_LAS unsigned char* lds, int wid, int lane) const {
;     ...
;         for (int bj = 0; bj < 2; ++bj)
; #pragma unroll
;             for (int n = 0; n < 2; ++n) {
;                 const int c = col0 + bj * HALF + n * 4;
;                 const f32x4 gg = *(const f32x4*)(gate + (size_t)b * 9216 + c) * *(const f32x4*)(gpost + c) * res_w;
; #pragma unroll
;                 for (int ai = 0; ai < 2; ++ai)
; #pragma unroll
;                     for (int m = 0; m < 4; ++m) { const int r = ai * HALF + wr * 64 + m * 16 + fr;
;                         const unsigned w0 = n ? pre[ai][m][bj].z : pre[ai][m][bj].x, w1 = n ? pre[ai][m][bj].w : pre[ai][m][bj].y;
;                         const f32x4 xv = {f16lo(w0), f16hi(w0), f16lo(w1), f16hi(w1)};
;                         acc[ai][bj][m][n] = xv + gg * (acc[ai][bj][m][n] * S[r]); }
;                 asm volatile("" ::: "memory");
;             }
;         if (HH) panel_rstd(acc, u, wr, wc, fr, fq, lds, wid, lane, xbuf + (size_t)16384 * 4, cnt, want1 + 32u, 1e-6f);
	v_pk_mul_f32 v[16:17], v[16:17], v[122:123] op_sel_hi:[1,0]
	s_nop 0
	v_pk_fma_f32 v[16:17], v[104:105], v[16:17], v[108:109]
	v_cvt_f32_f16_sdwa v109, v110 dst_sel:DWORD dst_unused:UNUSED_PAD src0_sel:WORD_1
	v_cvt_f32_f16_e32 v108, v110
	v_mov_b32_e32 v110, v123
	v_pk_mul_f32 v[18:19], v[18:19], v[122:123] op_sel_hi:[1,0]
	v_pk_mul_f32 v[12:13], v[12:13], v[110:111] op_sel_hi:[1,0]
	v_pk_fma_f32 v[18:19], v[100:101], v[18:19], v[120:121]
	v_cvt_f32_f16_sdwa v121, v111 dst_sel:DWORD dst_unused:UNUSED_PAD src0_sel:WORD_1
	v_cvt_f32_f16_e32 v120, v111
	v_pk_mul_f32 v[14:15], v[14:15], v[110:111] op_sel_hi:[1,0]
	v_pk_fma_f32 v[12:13], v[104:105], v[12:13], v[108:109]
	v_cvt_f32_f16_sdwa v109, v106 dst_sel:DWORD dst_unused:UNUSED_PAD src0_sel:WORD_1
	v_cvt_f32_f16_e32 v108, v106
	v_cvt_f32_f16_sdwa v111, v107 dst_sel:DWORD dst_unused:UNUSED_PAD src0_sel:WORD_1
	v_cvt_f32_f16_e32 v110, v107
	ds_read2_b32 v[106:107], v192 offset0:160 offset1:176
	v_pk_fma_f32 v[14:15], v[100:101], v[14:15], v[120:121]
	s_waitcnt lgkmcnt(0)
	v_pk_mul_f32 v[10:11], v[10:11], v[106:107] op_sel_hi:[1,0]
	v_pk_mul_f32 v[8:9], v[8:9], v[106:107] op_sel_hi:[1,0]
	v_pk_fma_f32 v[10:11], v[100:101], v[10:11], v[110:111]
	v_pk_fma_f32 v[8:9], v[104:105], v[8:9], v[108:109]
	v_cvt_f32_f16_sdwa v109, v102 dst_sel:DWORD dst_unused:UNUSED_PAD src0_sel:WORD_1
	v_cvt_f32_f16_e32 v108, v102
	v_cvt_f32_f16_sdwa v111, v103 dst_sel:DWORD dst_unused:UNUSED_PAD src0_sel:WORD_1
	v_cvt_f32_f16_e32 v110, v103
	v_mov_b32_e32 v102, v107
	v_pk_mul_f32 v[6:7], v[6:7], v[102:103] op_sel_hi:[1,0]
	v_pk_mul_f32 v[4:5], v[4:5], v[102:103] op_sel_hi:[1,0]
	v_pk_fma_f32 v[6:7], v[100:101], v[6:7], v[110:111]
	v_pk_fma_f32 v[4:5], v[104:105], v[4:5], v[108:109]
	s_cbranch_scc1 .LBB0_783
	v_mul_f32_e32 v100, v97, v97
	v_mul_f32_e32 v101, v99, v99
	v_fmac_f32_e32 v100, v96, v96
	v_fmac_f32_e32 v101, v98, v98
	v_add_f32_e32 v100, v100, v101
	v_mul_f32_e32 v101, v161, v161
	v_mul_f32_e32 v102, v163, v163
	v_fmac_f32_e32 v101, v160, v160
	v_fmac_f32_e32 v102, v162, v162
	v_add_f32_e32 v101, v101, v102
	v_add_f32_e32 v100, v100, v101
	v_mul_f32_e32 v101, v85, v85
	v_mul_f32_e32 v102, v87, v87
	v_fmac_f32_e32 v101, v84, v84
	v_fmac_f32_e32 v102, v86, v86
	v_add_f32_e32 v101, v101, v102
	v_add_f32_e32 v100, v100, v101
	v_mul_f32_e32 v101, v33, v33
	v_mul_f32_e32 v102, v35, v35
	v_fmac_f32_e32 v101, v32, v32
	v_fmac_f32_e32 v102, v34, v34
	v_add_f32_e32 v101, v101, v102
	v_add_f32_e32 v100, v100, v101
	v_mov_b32_e32 v101, v100
	s_nop 1
	v_permlane16_swap_b32_e32 v101, v100
	s_waitcnt lgkmcnt(0)
	v_add_f32_e32 v100, v100, v101
	v_mov_b32_e32 v101, v100
	s_nop 1
	v_permlane32_swap_b32_e32 v101, v100
	s_and_saveexec_b64 s[16:17], s[0:1]
	s_cbranch_execz .LBB0_756
	s_lshl_b32 s11, s38, 10
	s_add_i32 s11, s48, s11
	v_lshl_add_u32 v102, v219, 4, s11
	s_waitcnt lgkmcnt(0)
	v_add_f32_e32 v100, v100, v101
	ds_write_b32 v102, v100
.LBB0_756:
	s_or_b64 exec, exec, s[16:17]
	v_mul_f32_e32 v100, v89, v89
	s_waitcnt lgkmcnt(0)
	v_mul_f32_e32 v101, v91, v91
	v_fmac_f32_e32 v100, v88, v88
	v_fmac_f32_e32 v101, v90, v90
	v_add_f32_e32 v100, v100, v101
	v_mul_f32_e32 v101, v157, v157
	v_mul_f32_e32 v102, v159, v159
	v_fmac_f32_e32 v101, v156, v156
	v_fmac_f32_e32 v102, v158, v158
	v_add_f32_e32 v101, v101, v102
	v_add_f32_e32 v100, v100, v101
	v_mul_f32_e32 v101, v77, v77
	v_mul_f32_e32 v102, v79, v79
	v_fmac_f32_e32 v101, v76, v76
	v_fmac_f32_e32 v102, v78, v78
	v_add_f32_e32 v101, v101, v102
	v_add_f32_e32 v100, v100, v101
	v_mul_f32_e32 v101, v29, v29
	v_mul_f32_e32 v102, v31, v31
	v_fmac_f32_e32 v101, v28, v28
	v_fmac_f32_e32 v102, v30, v30
	v_add_f32_e32 v101, v101, v102
	v_add_f32_e32 v100, v100, v101
	v_mov_b32_e32 v101, v100
	s_nop 1
	v_permlane16_swap_b32_e32 v101, v100
	s_waitcnt lgkmcnt(0)
	v_add_f32_e32 v100, v100, v101
	v_mov_b32_e32 v101, v100
	s_nop 1
	v_permlane32_swap_b32_e32 v101, v100
	s_and_saveexec_b64 s[16:17], s[0:1]
	s_cbranch_execz .LBB0_758
	s_lshl_b32 s11, s38, 10
	s_add_i32 s11, s48, s11
	v_lshl_add_u32 v102, v219, 4, s11
	s_waitcnt lgkmcnt(0)
	v_add_f32_e32 v100, v100, v101
	ds_write_b32 v102, v100 offset:256
.LBB0_758:
	s_or_b64 exec, exec, s[16:17]
	v_mul_f32_e32 v100, v93, v93
	s_waitcnt lgkmcnt(0)
	v_mul_f32_e32 v101, v95, v95
	v_fmac_f32_e32 v100, v92, v92
	v_fmac_f32_e32 v101, v94, v94
	v_add_f32_e32 v100, v100, v101
	v_mul_f32_e32 v101, v153, v153
	v_mul_f32_e32 v102, v155, v155
	v_fmac_f32_e32 v101, v152, v152
	v_fmac_f32_e32 v102, v154, v154
	v_add_f32_e32 v101, v101, v102
	v_add_f32_e32 v100, v100, v101
	v_mul_f32_e32 v101, v61, v61
	v_mul_f32_e32 v102, v63, v63
	v_fmac_f32_e32 v101, v60, v60
	v_fmac_f32_e32 v102, v62, v62
	v_add_f32_e32 v101, v101, v102
	v_add_f32_e32 v100, v100, v101
	v_mul_f32_e32 v101, v25, v25
	v_mul_f32_e32 v102, v27, v27
	v_fmac_f32_e32 v101, v24, v24
	v_fmac_f32_e32 v102, v26, v26
	v_add_f32_e32 v101, v101, v102
	v_add_f32_e32 v100, v100, v101
	v_mov_b32_e32 v101, v100
	s_nop 1
	v_permlane16_swap_b32_e32 v101, v100
	s_waitcnt lgkmcnt(0)
	v_add_f32_e32 v100, v100, v101
	v_mov_b32_e32 v101, v100
	s_nop 1
	v_permlane32_swap_b32_e32 v101, v100
	s_and_saveexec_b64 s[16:17], s[0:1]
	s_cbranch_execz .LBB0_760
	s_lshl_b32 s11, s38, 10
	s_add_i32 s11, s48, s11
	v_lshl_add_u32 v102, v219, 4, s11
	s_waitcnt lgkmcnt(0)
	v_add_f32_e32 v100, v100, v101
	ds_write_b32 v102, v100 offset:512
; __device__ __forceinline__ void panel_rstd(const f32x4 (&v)[2][2][4][2], const Unit& u, int wr, int wc, int fr, int fq, PG8_LAS unsigned char* lds, int wid, int lane,
;                                            float* xslots, unsigned* cnt, unsigned want, float eps) {
;     ...
; #pragma unroll
;     for (int ai = 0; ai < 2; ++ai)
; #pragma unroll
;         for (int m = 0; m < 4; ++m) {
;             float s = 0.f;
; #pragma unroll
;             for (int bj = 0; bj < 2; ++bj)
; #pragma unroll
;                 for (int n = 0; n < 2; ++n) { const f32x4 x = v[ai][bj][m][n]; s += (x[0] * x[0] + x[1] * x[1]) + (x[2] * x[2] + x[3] * x[3]); }
;             s += __shfl_xor(s, 16); s += __shfl_xor(s, 32);
;             if (fq == 0) P[(ai * HALF + wr * 64 + m * 16 + fr) * 4 + wc] = s;
;         }
.LBB0_760:
	s_or_b64 exec, exec, s[16:17]
	v_mul_f32_e32 v100, v73, v73
	s_waitcnt lgkmcnt(0)
	v_mul_f32_e32 v101, v75, v75
	v_fmac_f32_e32 v100, v72, v72
	v_fmac_f32_e32 v101, v74, v74
	v_add_f32_e32 v100, v100, v101
	v_mul_f32_e32 v101, v149, v149
	v_mul_f32_e32 v102, v151, v151
	v_fmac_f32_e32 v101, v148, v148
	v_fmac_f32_e32 v102, v150, v150
	v_add_f32_e32 v101, v101, v102
	v_add_f32_e32 v100, v100, v101
	v_mul_f32_e32 v101, v57, v57
	v_mul_f32_e32 v102, v59, v59
	v_fmac_f32_e32 v101, v56, v56
	v_fmac_f32_e32 v102, v58, v58
	v_add_f32_e32 v101, v101, v102
	v_add_f32_e32 v100, v100, v101
	v_mul_f32_e32 v101, v21, v21
	v_mul_f32_e32 v102, v23, v23
	v_fmac_f32_e32 v101, v20, v20
	v_fmac_f32_e32 v102, v22, v22
	v_add_f32_e32 v101, v101, v102
	v_add_f32_e32 v100, v100, v101
	v_mov_b32_e32 v101, v100
	s_nop 1
	v_permlane16_swap_b32_e32 v101, v100
	s_waitcnt lgkmcnt(0)
	v_add_f32_e32 v100, v100, v101
	v_mov_b32_e32 v101, v100
	s_nop 1
	v_permlane32_swap_b32_e32 v101, v100
	s_and_saveexec_b64 s[16:17], s[0:1]
	s_cbranch_execz .LBB0_762
	s_lshl_b32 s11, s38, 10
	s_add_i32 s11, s48, s11
	v_lshl_add_u32 v102, v219, 4, s11
	s_waitcnt lgkmcnt(0)
	v_add_f32_e32 v100, v100, v101
	ds_write_b32 v102, v100 offset:768
.LBB0_762:
	s_or_b64 exec, exec, s[16:17]
	v_mul_f32_e32 v100, v81, v81
	s_waitcnt lgkmcnt(0)
	v_mul_f32_e32 v101, v83, v83
	v_fmac_f32_e32 v100, v80, v80
	v_fmac_f32_e32 v101, v82, v82
	v_add_f32_e32 v100, v100, v101
	v_mul_f32_e32 v101, v145, v145
	v_mul_f32_e32 v102, v147, v147
	v_fmac_f32_e32 v101, v144, v144
	v_fmac_f32_e32 v102, v146, v146
	v_add_f32_e32 v101, v101, v102
	v_add_f32_e32 v100, v100, v101
	v_mul_f32_e32 v101, v49, v49
	v_mul_f32_e32 v102, v51, v51
	v_fmac_f32_e32 v101, v48, v48
	v_fmac_f32_e32 v102, v50, v50
	v_add_f32_e32 v101, v101, v102
	v_add_f32_e32 v100, v100, v101
	v_mul_f32_e32 v101, v17, v17
	v_mul_f32_e32 v102, v19, v19
	v_fmac_f32_e32 v101, v16, v16
	v_fmac_f32_e32 v102, v18, v18
	v_add_f32_e32 v101, v101, v102
	v_add_f32_e32 v100, v100, v101
	v_mov_b32_e32 v101, v100
	s_nop 1
	v_permlane16_swap_b32_e32 v101, v100
	s_waitcnt lgkmcnt(0)
	v_add_f32_e32 v100, v100, v101
	v_mov_b32_e32 v101, v100
	s_nop 1
	v_permlane32_swap_b32_e32 v101, v100
	s_and_saveexec_b64 s[16:17], s[0:1]
	s_cbranch_execz .LBB0_764
	s_lshl_b32 s11, s38, 10
	s_add_i32 s11, s48, s11
	v_lshl_add_u32 v102, v219, 4, s11
	s_waitcnt lgkmcnt(0)
	v_add_f32_e32 v100, v100, v101
	ds_write_b32 v102, v100 offset:2048
.LBB0_764:
	s_or_b64 exec, exec, s[16:17]
	v_mul_f32_e32 v100, v65, v65
	s_waitcnt lgkmcnt(0)
	v_mul_f32_e32 v101, v67, v67
	v_fmac_f32_e32 v100, v64, v64
	v_fmac_f32_e32 v101, v66, v66
	v_add_f32_e32 v100, v100, v101
	v_mul_f32_e32 v101, v137, v137
	v_mul_f32_e32 v102, v139, v139
	v_fmac_f32_e32 v101, v136, v136
	v_fmac_f32_e32 v102, v138, v138
	v_add_f32_e32 v101, v101, v102
	v_add_f32_e32 v100, v100, v101
	v_mul_f32_e32 v101, v45, v45
	v_mul_f32_e32 v102, v47, v47
	v_fmac_f32_e32 v101, v44, v44
	v_fmac_f32_e32 v102, v46, v46
	v_add_f32_e32 v101, v101, v102
	v_add_f32_e32 v100, v100, v101
	v_mul_f32_e32 v101, v13, v13
	v_mul_f32_e32 v102, v15, v15
	v_fmac_f32_e32 v101, v12, v12
	v_fmac_f32_e32 v102, v14, v14
	v_add_f32_e32 v101, v101, v102
	v_add_f32_e32 v100, v100, v101
	v_mov_b32_e32 v101, v100
	s_nop 1
	v_permlane16_swap_b32_e32 v101, v100
	s_waitcnt lgkmcnt(0)
	v_add_f32_e32 v100, v100, v101
	v_mov_b32_e32 v101, v100
	s_nop 1
	v_permlane32_swap_b32_e32 v101, v100
	s_and_saveexec_b64 s[16:17], s[0:1]
	s_cbranch_execz .LBB0_766
	s_lshl_b32 s11, s38, 10
	s_add_i32 s11, s48, s11
	v_lshl_add_u32 v102, v219, 4, s11
	s_waitcnt lgkmcnt(0)
	v_add_f32_e32 v100, v100, v101
	ds_write_b32 v102, v100 offset:2304
.LBB0_766:
	s_or_b64 exec, exec, s[16:17]
	v_mul_f32_e32 v100, v69, v69
	s_waitcnt lgkmcnt(0)
	v_mul_f32_e32 v101, v71, v71
	v_fmac_f32_e32 v100, v68, v68
	v_fmac_f32_e32 v101, v70, v70
	v_add_f32_e32 v100, v100, v101
	v_mul_f32_e32 v101, v117, v117
	v_mul_f32_e32 v102, v119, v119
	v_fmac_f32_e32 v101, v116, v116
	v_fmac_f32_e32 v102, v118, v118
	v_add_f32_e32 v101, v101, v102
	v_add_f32_e32 v100, v100, v101
	v_mul_f32_e32 v101, v41, v41
	v_mul_f32_e32 v102, v43, v43
	v_fmac_f32_e32 v101, v40, v40
	v_fmac_f32_e32 v102, v42, v42
	v_add_f32_e32 v101, v101, v102
	v_add_f32_e32 v100, v100, v101
	v_mul_f32_e32 v101, v9, v9
	v_mul_f32_e32 v102, v11, v11
	v_fmac_f32_e32 v101, v8, v8
	v_fmac_f32_e32 v102, v10, v10
	v_add_f32_e32 v101, v101, v102
	v_add_f32_e32 v100, v100, v101
	v_mov_b32_e32 v101, v100
	s_nop 1
	v_permlane16_swap_b32_e32 v101, v100
	s_waitcnt lgkmcnt(0)
	v_add_f32_e32 v100, v100, v101
	v_mov_b32_e32 v101, v100
	s_nop 1
	v_permlane32_swap_b32_e32 v101, v100
	s_and_saveexec_b64 s[16:17], s[0:1]
	s_cbranch_execz .LBB0_768
	s_lshl_b32 s11, s38, 10
	s_add_i32 s11, s48, s11
	v_lshl_add_u32 v102, v219, 4, s11
	s_waitcnt lgkmcnt(0)
	v_add_f32_e32 v100, v100, v101
	ds_write_b32 v102, v100 offset:2560
.LBB0_768:
	s_or_b64 exec, exec, s[16:17]
	v_mul_f32_e32 v100, v53, v53
	s_waitcnt lgkmcnt(0)
	v_mul_f32_e32 v101, v55, v55
	v_fmac_f32_e32 v100, v52, v52
	v_fmac_f32_e32 v101, v54, v54
	v_add_f32_e32 v100, v100, v101
	v_mul_f32_e32 v101, v113, v113
	v_mul_f32_e32 v102, v115, v115
	v_fmac_f32_e32 v101, v112, v112
	v_fmac_f32_e32 v102, v114, v114
	v_add_f32_e32 v101, v101, v102
	v_add_f32_e32 v100, v100, v101
	v_mul_f32_e32 v101, v37, v37
	v_mul_f32_e32 v102, v39, v39
	v_fmac_f32_e32 v101, v36, v36
	v_fmac_f32_e32 v102, v38, v38
	v_add_f32_e32 v101, v101, v102
	v_add_f32_e32 v100, v100, v101
	v_mul_f32_e32 v101, v5, v5
	v_mul_f32_e32 v102, v7, v7
	v_fmac_f32_e32 v101, v4, v4
	v_fmac_f32_e32 v102, v6, v6
	v_add_f32_e32 v101, v101, v102
	v_add_f32_e32 v100, v100, v101
	v_mov_b32_e32 v2, v100
	s_nop 1
	v_permlane16_swap_b32_e32 v2, v100
	s_waitcnt lgkmcnt(0)
	v_add_f32_e32 v2, v100, v2
	v_mov_b32_e32 v100, v2
	s_nop 1
	v_permlane32_swap_b32_e32 v100, v2
	s_and_saveexec_b64 s[16:17], s[0:1]
	s_cbranch_execz .LBB0_770
	s_lshl_b32 s0, s38, 10
	s_add_i32 s48, s48, s0
	v_lshl_add_u32 v101, v219, 4, s48
	s_waitcnt lgkmcnt(0)
	v_add_f32_e32 v2, v2, v100
	ds_write_b32 v101, v2 offset:2816
